# attention item: output-gate loads issued at item start into spare VGPRs, copied in the epilogue (no load->wait at item end)
# speedup vs baseline: 1.0177x; 1.0028x over previous
.LBB0_1065:
	v_mov_b32_e32 v0, v33
	s_getreg_b32 s2, hwreg(HW_REG_HW_ID, 0, 6)
	s_lshl_b32 s2, s2, 2
	s_and_b32 s2, s2, 0xfc
	s_add_i32 s2, s2, 0
	s_add_i32 s2, s2, 0x21100
	v_mov_b32_e32 v1, s2
	ds_read_b32 v1, v1
	v_mbcnt_lo_u32_b32 v0, -1, v0
	v_mbcnt_hi_u32_b32 v0, -1, v0
	s_mov_b64 s[2:3], 0
	v_lshlrev_b32_e32 v36, 16, v203
	s_waitcnt lgkmcnt(0)
	v_lshl_or_b32 v2, v1, 6, v0
	s_add_u32 s2, s76, s2
	s_addc_u32 s3, s77, s3
	s_add_i32 s96, s96, s87
	v_and_or_b32 v0, v2, 31, s96
	v_or_b32_e32 v32, s97, v0
	v_lshlrev_b64 v[0:1], 12, v[32:33]
	v_lshl_add_u64 v[0:1], s[2:3], 0, v[0:1]
	v_lshrrev_b32_e32 v2, 2, v2
	v_lshl_add_u64 v[0:1], s[84:85], 1, v[0:1]
	v_and_b32_e32 v32, 8, v2
	v_lshl_add_u64 v[2:3], v[0:1], 0, v[32:33]
	s_mov_b64 s[2:3], 0x25e51000
	v_lshl_add_u64 v[0:1], v[2:3], 0, s[2:3]
	s_mov_b32 s2, 0x25e51000
	v_add_co_u32_e32 v4, vcc, s2, v2
	v_and_b32_e32 v37, 0xffff0000, v203
	s_nop 0
	v_addc_co_u32_e32 v5, vcc, 0, v3, vcc
	v_mov_b32_e32 v34, v212
	v_mov_b32_e32 v35, v213
	v_mov_b32_e32 v30, v214
	v_mov_b32_e32 v31, v215
	v_mov_b32_e32 v28, v216
	v_mov_b32_e32 v29, v217
	v_mov_b32_e32 v26, v218
	v_mov_b32_e32 v27, v219
	v_mov_b32_e32 v24, v220
	v_mov_b32_e32 v25, v221
	v_mov_b32_e32 v22, v222
	v_mov_b32_e32 v23, v223
	v_mov_b32_e32 v20, v224
	v_mov_b32_e32 v21, v225
	v_mov_b32_e32 v18, v226
	v_mov_b32_e32 v19, v227
	v_mov_b32_e32 v16, v236
	v_mov_b32_e32 v17, v237
	v_mov_b32_e32 v14, v238
	v_mov_b32_e32 v15, v239
	v_mov_b32_e32 v12, v240
	v_mov_b32_e32 v13, v241
	v_mov_b32_e32 v10, v242
	v_mov_b32_e32 v11, v243
	v_mov_b32_e32 v8, v244
	v_mov_b32_e32 v9, v245
	v_mov_b32_e32 v6, v246
	v_mov_b32_e32 v7, v247
	v_mov_b32_e32 v4, v248
	v_mov_b32_e32 v5, v249
	s_nop 0
	v_mov_b32_e32 v0, v250
	v_mov_b32_e32 v1, v251
	s_mov_b32 s2, 0x29e51000
	v_add_co_u32_e32 v2, vcc, s2, v2
	s_waitcnt vmcnt(0)
	v_lshlrev_b32_e32 v38, 16, v34
	v_mul_f32_e32 v32, 0xbfb8aa3b, v38
	v_exp_f32_e32 v32, v32
	v_and_b32_e32 v39, 0xffff0000, v34
	v_addc_co_u32_e32 v3, vcc, 0, v3, vcc
	v_mbcnt_lo_u32_b32 v252, -1, 0
	v_mbcnt_hi_u32_b32 v252, -1, v252
	v_and_b32_e32 v252, 32, v252
	v_lshrrev_b32_e32 v252, 2, v252
	v_mov_b32_e32 v253, 0
	v_lshl_add_u64 v[228:229], v[2:3], 0, v[252:253]
	v_add_f32_e32 v32, 1.0, v32
	v_rcp_f32_e32 v40, v32
	v_mul_f32_e32 v32, 0xbfb8aa3b, v39
	v_exp_f32_e32 v32, v32
	s_nop 0
	v_add_f32_e32 v32, 1.0, v32
	v_rcp_f32_e32 v41, v32
	s_nop 0
	v_pk_mul_f32 v[38:39], v[40:41], v[38:39]
	s_nop 0
	v_pk_mul_f32 v[36:37], v[38:39], v[36:37]
	v_lshlrev_b32_e32 v38, 16, v35
	v_mul_f32_e32 v32, 0xbfb8aa3b, v38
	v_exp_f32_e32 v32, v32
	v_and_b32_e32 v39, 0xffff0000, v35
	v_cvt_pk_bf16_f32 v34, v36, v37
	v_lshlrev_b32_e32 v36, 16, v202
	v_add_f32_e32 v32, 1.0, v32
	v_rcp_f32_e32 v40, v32
	v_mul_f32_e32 v32, 0xbfb8aa3b, v39
	v_exp_f32_e32 v32, v32
	v_and_b32_e32 v37, 0xffff0000, v202
	v_add_f32_e32 v32, 1.0, v32
	v_rcp_f32_e32 v41, v32
	s_nop 0
	v_pk_mul_f32 v[38:39], v[40:41], v[38:39]
	s_nop 0
	v_pk_mul_f32 v[36:37], v[38:39], v[36:37]
	s_nop 0
	v_cvt_pk_bf16_f32 v35, v36, v37
	v_lshlrev_b32_e32 v36, 16, v30
	v_and_b32_e32 v37, 0xffff0000, v30
	v_mul_f32_e32 v30, 0xbfb8aa3b, v36
	v_exp_f32_e32 v30, v30
	v_mov_b32_e32 v212, v34
	v_mov_b32_e32 v213, v35
	v_lshlrev_b32_e32 v34, 16, v201
	v_and_b32_e32 v35, 0xffff0000, v201
	v_add_f32_e32 v30, 1.0, v30
	v_rcp_f32_e32 v38, v30
	v_mul_f32_e32 v30, 0xbfb8aa3b, v37
	v_exp_f32_e32 v30, v30
	s_nop 0
	v_add_f32_e32 v30, 1.0, v30
	v_rcp_f32_e32 v39, v30
	s_nop 0
	v_pk_mul_f32 v[36:37], v[38:39], v[36:37]
	s_nop 0
	v_pk_mul_f32 v[34:35], v[36:37], v[34:35]
	v_lshlrev_b32_e32 v36, 16, v31
	v_and_b32_e32 v37, 0xffff0000, v31
	v_mul_f32_e32 v31, 0xbfb8aa3b, v36
	v_exp_f32_e32 v31, v31
	v_cvt_pk_bf16_f32 v30, v34, v35
	v_lshlrev_b32_e32 v34, 16, v200
	v_and_b32_e32 v35, 0xffff0000, v200
	v_add_f32_e32 v31, 1.0, v31
	v_rcp_f32_e32 v38, v31
	v_mul_f32_e32 v31, 0xbfb8aa3b, v37
	v_exp_f32_e32 v31, v31
	s_nop 0
	v_add_f32_e32 v31, 1.0, v31
	v_rcp_f32_e32 v39, v31
	s_nop 0
	v_pk_mul_f32 v[36:37], v[38:39], v[36:37]
	s_nop 0
	v_pk_mul_f32 v[34:35], v[36:37], v[34:35]
	s_nop 0
	v_cvt_pk_bf16_f32 v31, v34, v35
	v_lshlrev_b32_e32 v34, 16, v28
	v_and_b32_e32 v35, 0xffff0000, v28
	v_mul_f32_e32 v28, 0xbfb8aa3b, v34
	v_exp_f32_e32 v28, v28
	v_mov_b32_e32 v214, v30
	v_mov_b32_e32 v215, v31
	s_nop 1
	v_permlane32_swap_b32_e32 v212, v214
	v_permlane32_swap_b32_e32 v213, v215
	global_store_dwordx4 v[228:229], v[212:215], off
	v_lshlrev_b32_e32 v30, 16, v199
	v_and_b32_e32 v31, 0xffff0000, v199
	v_add_f32_e32 v28, 1.0, v28
	v_rcp_f32_e32 v36, v28
	v_mul_f32_e32 v28, 0xbfb8aa3b, v35
	v_exp_f32_e32 v28, v28
	s_nop 0
	v_add_f32_e32 v28, 1.0, v28
	v_rcp_f32_e32 v37, v28
	s_nop 0
	v_pk_mul_f32 v[34:35], v[36:37], v[34:35]
	s_nop 0
	v_pk_mul_f32 v[30:31], v[34:35], v[30:31]
	v_lshlrev_b32_e32 v34, 16, v29
	v_and_b32_e32 v35, 0xffff0000, v29
	v_mul_f32_e32 v29, 0xbfb8aa3b, v34
	v_exp_f32_e32 v29, v29
	v_cvt_pk_bf16_f32 v28, v30, v31
	v_lshlrev_b32_e32 v30, 16, v198
	v_and_b32_e32 v31, 0xffff0000, v198
	v_add_f32_e32 v29, 1.0, v29
	v_rcp_f32_e32 v36, v29
	v_mul_f32_e32 v29, 0xbfb8aa3b, v35
	v_exp_f32_e32 v29, v29
	s_nop 0
	v_add_f32_e32 v29, 1.0, v29
	v_rcp_f32_e32 v37, v29
	s_nop 0
	v_pk_mul_f32 v[34:35], v[36:37], v[34:35]
	s_nop 0
	v_pk_mul_f32 v[30:31], v[34:35], v[30:31]
	s_nop 0
	v_cvt_pk_bf16_f32 v29, v30, v31
	v_lshlrev_b32_e32 v30, 16, v26
	v_and_b32_e32 v31, 0xffff0000, v26
	v_mul_f32_e32 v26, 0xbfb8aa3b, v30
	v_exp_f32_e32 v26, v26
	v_mov_b32_e32 v216, v28
	v_mov_b32_e32 v217, v29
	v_lshlrev_b32_e32 v28, 16, v197
	v_and_b32_e32 v29, 0xffff0000, v197
	v_add_f32_e32 v26, 1.0, v26
	v_rcp_f32_e32 v34, v26
	v_mul_f32_e32 v26, 0xbfb8aa3b, v31
	v_exp_f32_e32 v26, v26
	s_nop 0
	v_add_f32_e32 v26, 1.0, v26
	v_rcp_f32_e32 v35, v26
	s_nop 0
	v_pk_mul_f32 v[30:31], v[34:35], v[30:31]
	s_nop 0
	v_pk_mul_f32 v[28:29], v[30:31], v[28:29]
	v_lshlrev_b32_e32 v30, 16, v27
	v_and_b32_e32 v31, 0xffff0000, v27
	v_mul_f32_e32 v27, 0xbfb8aa3b, v30
	v_exp_f32_e32 v27, v27
	v_cvt_pk_bf16_f32 v26, v28, v29
	v_lshlrev_b32_e32 v28, 16, v196
	v_and_b32_e32 v29, 0xffff0000, v196
	v_add_f32_e32 v27, 1.0, v27
	v_rcp_f32_e32 v34, v27
	v_mul_f32_e32 v27, 0xbfb8aa3b, v31
	v_exp_f32_e32 v27, v27
	s_nop 0
	v_add_f32_e32 v27, 1.0, v27
	v_rcp_f32_e32 v35, v27
	s_nop 0
	v_pk_mul_f32 v[30:31], v[34:35], v[30:31]
	s_nop 0
	v_pk_mul_f32 v[28:29], v[30:31], v[28:29]
	s_nop 0
	v_cvt_pk_bf16_f32 v27, v28, v29
	v_lshlrev_b32_e32 v28, 16, v24
	v_and_b32_e32 v29, 0xffff0000, v24
	v_mul_f32_e32 v24, 0xbfb8aa3b, v28
	v_exp_f32_e32 v24, v24
	v_mov_b32_e32 v218, v26
	v_mov_b32_e32 v219, v27
	s_nop 1
	v_permlane32_swap_b32_e32 v216, v218
	v_permlane32_swap_b32_e32 v217, v219
	global_store_dwordx4 v[228:229], v[216:219], off offset:32
	v_lshlrev_b32_e32 v26, 16, v195
	v_and_b32_e32 v27, 0xffff0000, v195
	v_add_f32_e32 v24, 1.0, v24
	v_rcp_f32_e32 v30, v24
	v_mul_f32_e32 v24, 0xbfb8aa3b, v29
	v_exp_f32_e32 v24, v24
	s_nop 0
	v_add_f32_e32 v24, 1.0, v24
	v_rcp_f32_e32 v31, v24
	s_nop 0
	v_pk_mul_f32 v[28:29], v[30:31], v[28:29]
	s_nop 0
	v_pk_mul_f32 v[26:27], v[28:29], v[26:27]
	v_lshlrev_b32_e32 v28, 16, v25
	v_and_b32_e32 v29, 0xffff0000, v25
	v_mul_f32_e32 v25, 0xbfb8aa3b, v28
	v_exp_f32_e32 v25, v25
	v_cvt_pk_bf16_f32 v24, v26, v27
	v_lshlrev_b32_e32 v26, 16, v194
	v_and_b32_e32 v27, 0xffff0000, v194
	v_add_f32_e32 v25, 1.0, v25
	v_rcp_f32_e32 v30, v25
	v_mul_f32_e32 v25, 0xbfb8aa3b, v29
	v_exp_f32_e32 v25, v25
	s_nop 0
	v_add_f32_e32 v25, 1.0, v25
	v_rcp_f32_e32 v31, v25
	s_nop 0
	v_pk_mul_f32 v[28:29], v[30:31], v[28:29]
	s_nop 0
	v_pk_mul_f32 v[26:27], v[28:29], v[26:27]
	s_nop 0
	v_cvt_pk_bf16_f32 v25, v26, v27
	v_lshlrev_b32_e32 v26, 16, v22
	v_and_b32_e32 v27, 0xffff0000, v22
	v_mul_f32_e32 v22, 0xbfb8aa3b, v26
	v_exp_f32_e32 v22, v22
	v_mov_b32_e32 v220, v24
	v_mov_b32_e32 v221, v25
	v_lshlrev_b32_e32 v24, 16, v193
	v_and_b32_e32 v25, 0xffff0000, v193
	v_add_f32_e32 v22, 1.0, v22
	v_rcp_f32_e32 v28, v22
	v_mul_f32_e32 v22, 0xbfb8aa3b, v27
	v_exp_f32_e32 v22, v22
	s_nop 0
	v_add_f32_e32 v22, 1.0, v22
	v_rcp_f32_e32 v29, v22
	s_nop 0
	v_pk_mul_f32 v[26:27], v[28:29], v[26:27]
	s_nop 0
	v_pk_mul_f32 v[24:25], v[26:27], v[24:25]
	v_lshlrev_b32_e32 v26, 16, v23
	v_and_b32_e32 v27, 0xffff0000, v23
	v_mul_f32_e32 v23, 0xbfb8aa3b, v26
	v_exp_f32_e32 v23, v23
	v_cvt_pk_bf16_f32 v22, v24, v25
	v_lshlrev_b32_e32 v24, 16, v192
	v_and_b32_e32 v25, 0xffff0000, v192
	v_add_f32_e32 v23, 1.0, v23
	v_rcp_f32_e32 v28, v23
	v_mul_f32_e32 v23, 0xbfb8aa3b, v27
	v_exp_f32_e32 v23, v23
	s_nop 0
	v_add_f32_e32 v23, 1.0, v23
	v_rcp_f32_e32 v29, v23
	s_nop 0
	v_pk_mul_f32 v[26:27], v[28:29], v[26:27]
	s_nop 0
	v_pk_mul_f32 v[24:25], v[26:27], v[24:25]
	s_nop 0
	v_cvt_pk_bf16_f32 v23, v24, v25
	v_lshlrev_b32_e32 v24, 16, v20
	v_and_b32_e32 v25, 0xffff0000, v20
	v_mul_f32_e32 v20, 0xbfb8aa3b, v24
	v_exp_f32_e32 v20, v20
	v_mov_b32_e32 v222, v22
	v_mov_b32_e32 v223, v23
	s_nop 1
	v_permlane32_swap_b32_e32 v220, v222
	v_permlane32_swap_b32_e32 v221, v223
	global_store_dwordx4 v[228:229], v[220:223], off offset:64
	v_lshlrev_b32_e32 v22, 16, v191
	v_and_b32_e32 v23, 0xffff0000, v191
	v_add_f32_e32 v20, 1.0, v20
	v_rcp_f32_e32 v26, v20
	v_mul_f32_e32 v20, 0xbfb8aa3b, v25
	v_exp_f32_e32 v20, v20
	s_nop 0
	v_add_f32_e32 v20, 1.0, v20
	v_rcp_f32_e32 v27, v20
	s_nop 0
	v_pk_mul_f32 v[24:25], v[26:27], v[24:25]
	s_nop 0
	v_pk_mul_f32 v[22:23], v[24:25], v[22:23]
	v_lshlrev_b32_e32 v24, 16, v21
	v_and_b32_e32 v25, 0xffff0000, v21
	v_mul_f32_e32 v21, 0xbfb8aa3b, v24
	v_exp_f32_e32 v21, v21
	v_cvt_pk_bf16_f32 v20, v22, v23
	v_lshlrev_b32_e32 v22, 16, v190
	v_and_b32_e32 v23, 0xffff0000, v190
	v_add_f32_e32 v21, 1.0, v21
	v_rcp_f32_e32 v26, v21
	v_mul_f32_e32 v21, 0xbfb8aa3b, v25
	v_exp_f32_e32 v21, v21
	s_nop 0
	v_add_f32_e32 v21, 1.0, v21
	v_rcp_f32_e32 v27, v21
	s_nop 0
	v_pk_mul_f32 v[24:25], v[26:27], v[24:25]
	s_nop 0
	v_pk_mul_f32 v[22:23], v[24:25], v[22:23]
	s_nop 0
	v_cvt_pk_bf16_f32 v21, v22, v23
	v_lshlrev_b32_e32 v22, 16, v18
	v_and_b32_e32 v23, 0xffff0000, v18
	v_mul_f32_e32 v18, 0xbfb8aa3b, v22
	v_exp_f32_e32 v18, v18
	v_mov_b32_e32 v224, v20
	v_mov_b32_e32 v225, v21
	v_lshlrev_b32_e32 v20, 16, v189
	v_and_b32_e32 v21, 0xffff0000, v189
	v_add_f32_e32 v18, 1.0, v18
	v_rcp_f32_e32 v24, v18
	v_mul_f32_e32 v18, 0xbfb8aa3b, v23
	v_exp_f32_e32 v18, v18
	s_nop 0
	v_add_f32_e32 v18, 1.0, v18
	v_rcp_f32_e32 v25, v18
	s_nop 0
	v_pk_mul_f32 v[22:23], v[24:25], v[22:23]
	s_nop 0
	v_pk_mul_f32 v[20:21], v[22:23], v[20:21]
	v_lshlrev_b32_e32 v22, 16, v19
	v_and_b32_e32 v23, 0xffff0000, v19
	v_mul_f32_e32 v19, 0xbfb8aa3b, v22
	v_exp_f32_e32 v19, v19
	v_cvt_pk_bf16_f32 v18, v20, v21
	v_lshlrev_b32_e32 v20, 16, v188
	v_and_b32_e32 v21, 0xffff0000, v188
	v_add_f32_e32 v19, 1.0, v19
	v_rcp_f32_e32 v24, v19
	v_mul_f32_e32 v19, 0xbfb8aa3b, v23
	v_exp_f32_e32 v19, v19
	s_nop 0
	v_add_f32_e32 v19, 1.0, v19
	v_rcp_f32_e32 v25, v19
	s_nop 0
	v_pk_mul_f32 v[22:23], v[24:25], v[22:23]
	s_nop 0
	v_pk_mul_f32 v[20:21], v[22:23], v[20:21]
	s_nop 0
	v_cvt_pk_bf16_f32 v19, v20, v21
	v_lshlrev_b32_e32 v20, 16, v16
	v_and_b32_e32 v21, 0xffff0000, v16
	v_mul_f32_e32 v16, 0xbfb8aa3b, v20
	v_exp_f32_e32 v16, v16
	v_mov_b32_e32 v226, v18
	v_mov_b32_e32 v227, v19
	s_nop 1
	v_permlane32_swap_b32_e32 v224, v226
	v_permlane32_swap_b32_e32 v225, v227
	global_store_dwordx4 v[228:229], v[224:227], off offset:96
	v_lshlrev_b32_e32 v18, 16, v187
	v_and_b32_e32 v19, 0xffff0000, v187
	v_add_f32_e32 v16, 1.0, v16
	v_rcp_f32_e32 v22, v16
	v_mul_f32_e32 v16, 0xbfb8aa3b, v21
	v_exp_f32_e32 v16, v16
	s_nop 0
	v_add_f32_e32 v16, 1.0, v16
	v_rcp_f32_e32 v23, v16
	s_nop 0
	v_pk_mul_f32 v[20:21], v[22:23], v[20:21]
	s_nop 0
	v_pk_mul_f32 v[18:19], v[20:21], v[18:19]
	v_lshlrev_b32_e32 v20, 16, v17
	v_and_b32_e32 v21, 0xffff0000, v17
	v_mul_f32_e32 v17, 0xbfb8aa3b, v20
	v_exp_f32_e32 v17, v17
	v_cvt_pk_bf16_f32 v16, v18, v19
	v_lshlrev_b32_e32 v18, 16, v186
	v_and_b32_e32 v19, 0xffff0000, v186
	v_add_f32_e32 v17, 1.0, v17
	v_rcp_f32_e32 v22, v17
	v_mul_f32_e32 v17, 0xbfb8aa3b, v21
	v_exp_f32_e32 v17, v17
	s_nop 0
	v_add_f32_e32 v17, 1.0, v17
	v_rcp_f32_e32 v23, v17
	s_nop 0
	v_pk_mul_f32 v[20:21], v[22:23], v[20:21]
	s_nop 0
	v_pk_mul_f32 v[18:19], v[20:21], v[18:19]
	s_nop 0
	v_cvt_pk_bf16_f32 v17, v18, v19
	v_lshlrev_b32_e32 v18, 16, v14
	v_and_b32_e32 v19, 0xffff0000, v14
	v_mul_f32_e32 v14, 0xbfb8aa3b, v18
	v_exp_f32_e32 v14, v14
	v_mov_b32_e32 v236, v16
	v_mov_b32_e32 v237, v17
	v_lshlrev_b32_e32 v16, 16, v185
	v_and_b32_e32 v17, 0xffff0000, v185
	v_add_f32_e32 v14, 1.0, v14
	v_rcp_f32_e32 v20, v14
	v_mul_f32_e32 v14, 0xbfb8aa3b, v19
	v_exp_f32_e32 v14, v14
	s_nop 0
	v_add_f32_e32 v14, 1.0, v14
	v_rcp_f32_e32 v21, v14
	s_nop 0
	v_pk_mul_f32 v[18:19], v[20:21], v[18:19]
	s_nop 0
	v_pk_mul_f32 v[16:17], v[18:19], v[16:17]
	v_lshlrev_b32_e32 v18, 16, v15
	v_and_b32_e32 v19, 0xffff0000, v15
	v_mul_f32_e32 v15, 0xbfb8aa3b, v18
	v_exp_f32_e32 v15, v15
	v_cvt_pk_bf16_f32 v14, v16, v17
	v_lshlrev_b32_e32 v16, 16, v184
	v_and_b32_e32 v17, 0xffff0000, v184
	v_add_f32_e32 v15, 1.0, v15
	v_rcp_f32_e32 v20, v15
	v_mul_f32_e32 v15, 0xbfb8aa3b, v19
	v_exp_f32_e32 v15, v15
	s_nop 0
	v_add_f32_e32 v15, 1.0, v15
	v_rcp_f32_e32 v21, v15
	s_nop 0
	v_pk_mul_f32 v[18:19], v[20:21], v[18:19]
	s_nop 0
	v_pk_mul_f32 v[16:17], v[18:19], v[16:17]
	s_nop 0
	v_cvt_pk_bf16_f32 v15, v16, v17
	v_lshlrev_b32_e32 v16, 16, v12
	v_and_b32_e32 v17, 0xffff0000, v12
	v_mul_f32_e32 v12, 0xbfb8aa3b, v16
	v_exp_f32_e32 v12, v12
	v_mov_b32_e32 v238, v14
	v_mov_b32_e32 v239, v15
	s_nop 1
	v_permlane32_swap_b32_e32 v236, v238
	v_permlane32_swap_b32_e32 v237, v239
	global_store_dwordx4 v[228:229], v[236:239], off offset:128
	v_lshlrev_b32_e32 v14, 16, v183
	v_and_b32_e32 v15, 0xffff0000, v183
	v_add_f32_e32 v12, 1.0, v12
	v_rcp_f32_e32 v18, v12
	v_mul_f32_e32 v12, 0xbfb8aa3b, v17
	v_exp_f32_e32 v12, v12
	s_nop 0
	v_add_f32_e32 v12, 1.0, v12
	v_rcp_f32_e32 v19, v12
	s_nop 0
	v_pk_mul_f32 v[16:17], v[18:19], v[16:17]
	s_nop 0
	v_pk_mul_f32 v[14:15], v[16:17], v[14:15]
	v_lshlrev_b32_e32 v16, 16, v13
	v_and_b32_e32 v17, 0xffff0000, v13
	v_mul_f32_e32 v13, 0xbfb8aa3b, v16
	v_exp_f32_e32 v13, v13
	v_cvt_pk_bf16_f32 v12, v14, v15
	v_lshlrev_b32_e32 v14, 16, v182
	v_and_b32_e32 v15, 0xffff0000, v182
	v_add_f32_e32 v13, 1.0, v13
	v_rcp_f32_e32 v18, v13
	v_mul_f32_e32 v13, 0xbfb8aa3b, v17
	v_exp_f32_e32 v13, v13
	s_nop 0
	v_add_f32_e32 v13, 1.0, v13
	v_rcp_f32_e32 v19, v13
	s_nop 0
	v_pk_mul_f32 v[16:17], v[18:19], v[16:17]
	s_nop 0
	v_pk_mul_f32 v[14:15], v[16:17], v[14:15]
	s_nop 0
	v_cvt_pk_bf16_f32 v13, v14, v15
	v_lshlrev_b32_e32 v14, 16, v10
	v_and_b32_e32 v15, 0xffff0000, v10
	v_mul_f32_e32 v10, 0xbfb8aa3b, v14
	v_exp_f32_e32 v10, v10
	v_mov_b32_e32 v240, v12
	v_mov_b32_e32 v241, v13
	v_lshlrev_b32_e32 v12, 16, v181
	v_and_b32_e32 v13, 0xffff0000, v181
	v_add_f32_e32 v10, 1.0, v10
	v_rcp_f32_e32 v16, v10
	v_mul_f32_e32 v10, 0xbfb8aa3b, v15
	v_exp_f32_e32 v10, v10
	s_nop 0
	v_add_f32_e32 v10, 1.0, v10
	v_rcp_f32_e32 v17, v10
	s_nop 0
	v_pk_mul_f32 v[14:15], v[16:17], v[14:15]
	s_nop 0
	v_pk_mul_f32 v[12:13], v[14:15], v[12:13]
	v_lshlrev_b32_e32 v14, 16, v11
	v_and_b32_e32 v15, 0xffff0000, v11
	v_mul_f32_e32 v11, 0xbfb8aa3b, v14
	v_exp_f32_e32 v11, v11
	v_cvt_pk_bf16_f32 v10, v12, v13
	v_lshlrev_b32_e32 v12, 16, v180
	v_and_b32_e32 v13, 0xffff0000, v180
	v_add_f32_e32 v11, 1.0, v11
	v_rcp_f32_e32 v16, v11
	v_mul_f32_e32 v11, 0xbfb8aa3b, v15
	v_exp_f32_e32 v11, v11
	s_nop 0
	v_add_f32_e32 v11, 1.0, v11
	v_rcp_f32_e32 v17, v11
	s_nop 0
	v_pk_mul_f32 v[14:15], v[16:17], v[14:15]
	s_nop 0
	v_pk_mul_f32 v[12:13], v[14:15], v[12:13]
	s_nop 0
	v_cvt_pk_bf16_f32 v11, v12, v13
	v_lshlrev_b32_e32 v12, 16, v8
	v_and_b32_e32 v13, 0xffff0000, v8
	v_mul_f32_e32 v8, 0xbfb8aa3b, v12
	v_exp_f32_e32 v8, v8
	v_mov_b32_e32 v242, v10
	v_mov_b32_e32 v243, v11
	s_nop 1
	v_permlane32_swap_b32_e32 v240, v242
	v_permlane32_swap_b32_e32 v241, v243
	global_store_dwordx4 v[228:229], v[240:243], off offset:160
	v_lshlrev_b32_e32 v10, 16, v177
	v_and_b32_e32 v11, 0xffff0000, v177
	v_add_f32_e32 v8, 1.0, v8
	v_rcp_f32_e32 v14, v8
	v_mul_f32_e32 v8, 0xbfb8aa3b, v13
	v_exp_f32_e32 v8, v8
	s_nop 0
	v_add_f32_e32 v8, 1.0, v8
	v_rcp_f32_e32 v15, v8
	s_nop 0
	v_pk_mul_f32 v[12:13], v[14:15], v[12:13]
	s_nop 0
	v_pk_mul_f32 v[10:11], v[12:13], v[10:11]
	v_lshlrev_b32_e32 v12, 16, v9
	v_and_b32_e32 v13, 0xffff0000, v9
	v_mul_f32_e32 v9, 0xbfb8aa3b, v12
	v_exp_f32_e32 v9, v9
	v_cvt_pk_bf16_f32 v8, v10, v11
	v_lshlrev_b32_e32 v10, 16, v176
	v_and_b32_e32 v11, 0xffff0000, v176
	v_add_f32_e32 v9, 1.0, v9
	v_rcp_f32_e32 v14, v9
	v_mul_f32_e32 v9, 0xbfb8aa3b, v13
	v_exp_f32_e32 v9, v9
	s_nop 0
	v_add_f32_e32 v9, 1.0, v9
	v_rcp_f32_e32 v15, v9
	s_nop 0
	v_pk_mul_f32 v[12:13], v[14:15], v[12:13]
	s_nop 0
	v_pk_mul_f32 v[10:11], v[12:13], v[10:11]
	s_nop 0
	v_cvt_pk_bf16_f32 v9, v10, v11
	v_lshlrev_b32_e32 v10, 16, v6
	v_and_b32_e32 v11, 0xffff0000, v6
	v_mul_f32_e32 v6, 0xbfb8aa3b, v10
	v_exp_f32_e32 v6, v6
	v_mov_b32_e32 v244, v8
	v_mov_b32_e32 v245, v9
	v_lshlrev_b32_e32 v8, 16, v175
	v_and_b32_e32 v9, 0xffff0000, v175
	v_add_f32_e32 v6, 1.0, v6
	v_rcp_f32_e32 v12, v6
	v_mul_f32_e32 v6, 0xbfb8aa3b, v11
	v_exp_f32_e32 v6, v6
	s_nop 0
	v_add_f32_e32 v6, 1.0, v6
	v_rcp_f32_e32 v13, v6
	s_nop 0
	v_pk_mul_f32 v[10:11], v[12:13], v[10:11]
	s_nop 0
	v_pk_mul_f32 v[8:9], v[10:11], v[8:9]
	v_lshlrev_b32_e32 v10, 16, v7
	v_and_b32_e32 v11, 0xffff0000, v7
	v_mul_f32_e32 v7, 0xbfb8aa3b, v10
	v_exp_f32_e32 v7, v7
	v_cvt_pk_bf16_f32 v6, v8, v9
	v_lshlrev_b32_e32 v8, 16, v174
	v_and_b32_e32 v9, 0xffff0000, v174
	v_add_f32_e32 v7, 1.0, v7
	v_rcp_f32_e32 v12, v7
	v_mul_f32_e32 v7, 0xbfb8aa3b, v11
	v_exp_f32_e32 v7, v7
	s_nop 0
	v_add_f32_e32 v7, 1.0, v7
	v_rcp_f32_e32 v13, v7
	s_nop 0
	v_pk_mul_f32 v[10:11], v[12:13], v[10:11]
	s_nop 0
	v_pk_mul_f32 v[8:9], v[10:11], v[8:9]
	s_nop 0
	v_cvt_pk_bf16_f32 v7, v8, v9
	v_lshlrev_b32_e32 v8, 16, v4
	v_and_b32_e32 v9, 0xffff0000, v4
	v_mul_f32_e32 v4, 0xbfb8aa3b, v8
	v_exp_f32_e32 v4, v4
	v_mov_b32_e32 v246, v6
	v_mov_b32_e32 v247, v7
	s_nop 1
	v_permlane32_swap_b32_e32 v244, v246
	v_permlane32_swap_b32_e32 v245, v247
	global_store_dwordx4 v[228:229], v[244:247], off offset:192
	v_lshlrev_b32_e32 v6, 16, v173
	v_and_b32_e32 v7, 0xffff0000, v173
	v_add_f32_e32 v4, 1.0, v4
	v_rcp_f32_e32 v10, v4
	v_mul_f32_e32 v4, 0xbfb8aa3b, v9
	v_exp_f32_e32 v4, v4
	s_nop 0
	v_add_f32_e32 v4, 1.0, v4
	v_rcp_f32_e32 v11, v4
	s_nop 0
	v_pk_mul_f32 v[8:9], v[10:11], v[8:9]
	s_nop 0
	v_pk_mul_f32 v[6:7], v[8:9], v[6:7]
	v_lshlrev_b32_e32 v8, 16, v5
	v_and_b32_e32 v9, 0xffff0000, v5
	v_mul_f32_e32 v5, 0xbfb8aa3b, v8
	v_exp_f32_e32 v5, v5
	v_cvt_pk_bf16_f32 v4, v6, v7
	v_lshlrev_b32_e32 v6, 16, v172
	v_and_b32_e32 v7, 0xffff0000, v172
	v_add_f32_e32 v5, 1.0, v5
	v_rcp_f32_e32 v10, v5
	v_mul_f32_e32 v5, 0xbfb8aa3b, v9
	v_exp_f32_e32 v5, v5
	s_nop 0
	v_add_f32_e32 v5, 1.0, v5
	v_rcp_f32_e32 v11, v5
	s_nop 0
	v_pk_mul_f32 v[8:9], v[10:11], v[8:9]
	s_nop 0
	v_pk_mul_f32 v[6:7], v[8:9], v[6:7]
	s_nop 0
	v_cvt_pk_bf16_f32 v5, v6, v7
	v_lshlrev_b32_e32 v6, 16, v0
	v_and_b32_e32 v7, 0xffff0000, v0
	v_mul_f32_e32 v0, 0xbfb8aa3b, v6
	v_exp_f32_e32 v0, v0
	v_mov_b32_e32 v248, v4
	v_mov_b32_e32 v249, v5
	v_lshlrev_b32_e32 v4, 16, v171
	v_and_b32_e32 v5, 0xffff0000, v171
	v_add_f32_e32 v0, 1.0, v0
	v_rcp_f32_e32 v8, v0
	v_mul_f32_e32 v0, 0xbfb8aa3b, v7
	v_exp_f32_e32 v0, v0
	s_nop 0
	v_add_f32_e32 v0, 1.0, v0
	v_rcp_f32_e32 v9, v0
	s_nop 0
	v_pk_mul_f32 v[6:7], v[8:9], v[6:7]
	s_nop 0
	v_pk_mul_f32 v[4:5], v[6:7], v[4:5]
	v_lshlrev_b32_e32 v6, 16, v1
	v_and_b32_e32 v7, 0xffff0000, v1
	v_mul_f32_e32 v1, 0xbfb8aa3b, v6
	v_exp_f32_e32 v1, v1
	v_cvt_pk_bf16_f32 v0, v4, v5
	v_lshlrev_b32_e32 v4, 16, v170
	v_and_b32_e32 v5, 0xffff0000, v170
	v_add_f32_e32 v1, 1.0, v1
	v_rcp_f32_e32 v8, v1
	v_mul_f32_e32 v1, 0xbfb8aa3b, v7
	v_exp_f32_e32 v1, v1
	s_nop 0
	v_add_f32_e32 v1, 1.0, v1
	v_rcp_f32_e32 v9, v1
	s_nop 0
	v_pk_mul_f32 v[6:7], v[8:9], v[6:7]
	s_nop 0
	v_pk_mul_f32 v[4:5], v[6:7], v[4:5]
	s_nop 0
	v_cvt_pk_bf16_f32 v1, v4, v5
	v_mov_b32_e32 v250, v0
	v_mov_b32_e32 v251, v1
	s_nop 1
	v_permlane32_swap_b32_e32 v248, v250
	v_permlane32_swap_b32_e32 v249, v251
	global_store_dwordx4 v[228:229], v[248:251], off offset:224

.LBB0_1077:
	s_or_b64 exec, exec, s[4:5]
	s_add_u32 s80, s76, s2
	s_addc_u32 s81, s77, s3
	s_ashr_i32 s17, s14, 6
	s_lshl_b32 s2, s93, 2
	s_lshl_b32 s3, s17, 5
	v_ashrrev_i32_e32 v1, 7, v129
	s_ashr_i32 s11, s14, 7
	s_and_b32 s2, s2, 12
	s_and_b32 s97, s3, 32
	s_lshl_b32 s3, s93, 9
	v_lshlrev_b32_e32 v0, 4, v0
	s_add_i32 s10, s11, s2
	s_and_b32 s87, s3, 0x3800
	v_add3_u32 v0, v1, s2, v0
	s_load_dwordx2 s[2:3], s[0:1], 0x10
	v_ashrrev_i32_e32 v1, 31, v0
	v_and_b32_e32 v18, 31, v129
	s_lshl_b32 s96, s79, 6
	v_or_b32_e32 v126, s97, v18
	s_waitcnt lgkmcnt(0)
	v_lshl_add_u64 v[0:1], v[0:1], 2, s[2:3]
	global_load_dword v0, v[0:1], off
	v_or_b32_e32 v125, s96, v126
	s_add_i32 s86, 0, 0x10000
	v_add_u32_e32 v32, s87, v125
	v_lshl_add_u32 v1, v129, 2, s86
	s_lshl_b32 s84, s10, 7
	v_bfe_u32 v124, v129, 5, 1
	s_ashr_i32 s85, s84, 31
	v_mbcnt_lo_u32_b32 v252, -1, 0
	v_mbcnt_hi_u32_b32 v252, -1, v252
	s_add_i32 s98, s96, s87
	v_and_or_b32 v228, v252, 31, s98
	v_or_b32_e32 v228, s97, v228
	v_mov_b32_e32 v229, 0
	v_lshlrev_b64 v[228:229], 12, v[228:229]
	v_lshl_add_u64 v[228:229], s[76:77], 0, v[228:229]
	v_lshl_add_u64 v[228:229], s[84:85], 1, v[228:229]
	v_lshrrev_b32_e32 v252, 2, v252
	v_and_b32_e32 v252, 8, v252
	v_mov_b32_e32 v253, 0
	v_lshl_add_u64 v[228:229], v[228:229], 0, v[252:253]
	s_mov_b64 s[98:99], 0x25e51000
	v_lshl_add_u64 v[228:229], v[228:229], 0, s[98:99]
	global_load_dwordx2 v[212:213], v[228:229], off
	global_load_dwordx2 v[214:215], v[228:229], off offset:16
	global_load_dwordx2 v[216:217], v[228:229], off offset:32
	global_load_dwordx2 v[218:219], v[228:229], off offset:48
	global_load_dwordx2 v[220:221], v[228:229], off offset:64
	global_load_dwordx2 v[222:223], v[228:229], off offset:80
	global_load_dwordx2 v[224:225], v[228:229], off offset:96
	global_load_dwordx2 v[226:227], v[228:229], off offset:112
	global_load_dwordx2 v[236:237], v[228:229], off offset:128
	global_load_dwordx2 v[238:239], v[228:229], off offset:144
	global_load_dwordx2 v[240:241], v[228:229], off offset:160
	global_load_dwordx2 v[242:243], v[228:229], off offset:176
	global_load_dwordx2 v[244:245], v[228:229], off offset:192
	global_load_dwordx2 v[246:247], v[228:229], off offset:208
	global_load_dwordx2 v[248:249], v[228:229], off offset:224
	global_load_dwordx2 v[250:251], v[228:229], off offset:240
	v_lshlrev_b32_e32 v2, 4, v124
	v_mov_b32_e32 v3, v33
	s_mov_b64 s[2:3], 0x21e51000
	s_and_b32 s92, s93, 31
	v_and_b32_e32 v19, 63, v129
	v_lshlrev_b32_e32 v20, 11, v124
	v_lshlrev_b32_e32 v16, 7, v124
	v_sub_u32_e32 v39, v125, v16
	v_max_i32_e32 v17, 31, v39
	v_max_i32_e32 v21, 47, v39
	v_subrev_u32_e32 v17, 31, v17
	v_subrev_u32_e32 v21, 47, v21
	v_min_u32_e32 v17, 0x7f, v17
	v_min_u32_e32 v21, 0x7f, v21
	s_waitcnt vmcnt(0)
	v_mul_f32_e32 v0, 0x3fb8aa3b, v0
	ds_write_b32 v1, v0
	v_lshlrev_b64 v[0:1], 12, v[32:33]
	v_lshl_add_u64 v[0:1], s[80:81], 0, v[0:1]
	v_lshl_add_u64 v[0:1], s[84:85], 1, v[0:1]
	v_lshl_add_u64 v[0:1], v[0:1], 0, v[2:3]
	v_lshl_add_u64 v[2:3], v[0:1], 0, s[2:3]
	s_mov_b32 s2, 0x21e51000
	v_add_co_u32_e32 v0, vcc, s2, v0
	s_lshl_b32 s2, s92, 15
	s_nop 0
	v_addc_co_u32_e32 v1, vcc, 0, v1, vcc
	global_load_dwordx4 v[130:133], v[0:1], off
	global_load_dwordx4 v[134:137], v[2:3], off offset:32
	global_load_dwordx4 v[138:141], v[2:3], off offset:64
	global_load_dwordx4 v[142:145], v[2:3], off offset:96
	global_load_dwordx4 v[146:149], v[2:3], off offset:128
	global_load_dwordx4 v[150:153], v[2:3], off offset:160
	global_load_dwordx4 v[154:157], v[2:3], off offset:192
	global_load_dwordx4 v[158:161], v[2:3], off offset:224
	s_add_u32 s4, s80, s2
	s_addc_u32 s5, s81, 0
	s_lshl_b32 s12, s17, 11
	s_ashr_i32 s13, s12, 31
	s_lshl_b64 s[2:3], s[12:13], 1
	s_add_u32 s2, s4, s2
	s_addc_u32 s3, s5, s3
	v_lshlrev_b32_e32 v0, 4, v19
	v_mov_b32_e32 v1, v33
	v_lshl_add_u64 v[0:1], s[2:3], 0, v[0:1]
	s_mov_b64 s[2:3], 0x4c359000
	v_lshl_add_u64 v[2:3], v[0:1], 0, s[2:3]
	s_lshl_b32 s2, s17, 12
	s_add_i32 s2, s2, 0
	s_mov_b32 m0, s2
	s_mov_b64 s[4:5], 0x4c359400
	global_load_lds_dwordx4 v[2:3], off
	v_lshl_add_u64 v[2:3], v[0:1], 0, s[4:5]
	s_add_i32 m0, s2, 0x400
	s_mov_b64 s[4:5], 0x4c359800
	global_load_lds_dwordx4 v[2:3], off
	v_lshl_add_u64 v[2:3], v[0:1], 0, s[4:5]
	s_add_i32 m0, s2, 0x800
	s_mov_b64 s[4:5], 0x4c359c00
	global_load_lds_dwordx4 v[2:3], off
	v_lshl_add_u64 v[2:3], v[0:1], 0, s[4:5]
	s_add_i32 m0, s2, 0xc00
	s_mov_b64 s[4:5], 0x4c459000
	global_load_lds_dwordx4 v[2:3], off
	v_lshl_add_u64 v[2:3], v[0:1], 0, s[4:5]
	s_add_i32 m0, s2, 0x8000
	s_mov_b64 s[4:5], 0x4c459400
	global_load_lds_dwordx4 v[2:3], off
	v_lshl_add_u64 v[2:3], v[0:1], 0, s[4:5]
	s_add_i32 m0, s2, 0x8400
	s_mov_b64 s[4:5], 0x4c459800
	global_load_lds_dwordx4 v[2:3], off
	v_lshl_add_u64 v[2:3], v[0:1], 0, s[4:5]
	s_add_i32 m0, s2, 0x8800
	s_mov_b64 s[4:5], 0x4c459c00
	global_load_lds_dwordx4 v[2:3], off
	v_lshl_add_u64 v[0:1], v[0:1], 0, s[4:5]
	s_add_i32 m0, s2, 0x8c00
	v_lshlrev_b32_e32 v2, 1, v129
	global_load_lds_dwordx4 v[0:1], off
	v_lshrrev_b32_e32 v1, 1, v129
	v_and_b32_e32 v0, 19, v129
	v_and_b32_e32 v1, 4, v1
	v_and_b32_e32 v2, 8, v2
	v_or3_b32 v0, v0, v1, v2
	v_lshl_add_u32 v127, v0, 4, 0
	s_waitcnt vmcnt(0) lgkmcnt(0)
	s_barrier
	v_add_u32_e32 v40, v127, v20
	ds_read_b128 v[0:3], v40
	ds_read_b128 v[22:25], v40 offset:4096
	s_waitcnt vmcnt(0) lgkmcnt(0)
	v_mfma_f32_32x32x16_bf16 v[0:15], v[0:3], v[130:133], 0
	s_and_b32 s2, s14, 0x3fffff80
	s_lshl_b32 s2, s2, 2
	s_add_i32 s86, s86, s2
	v_lshl_add_u32 v17, v17, 2, s86
	v_lshl_add_u32 v21, v21, 2, s86
	s_cmp_gt_u32 s79, 7
	s_cselect_b64 s[4:5], -1, 0
	v_mfma_f32_32x32x16_bf16 v[0:15], v[22:25], v[134:137], v[0:15]
	ds_read_b128 v[22:25], v40 offset:8192
	s_cmp_lt_u32 s79, 8
	s_waitcnt lgkmcnt(0)
	v_mfma_f32_32x32x16_bf16 v[0:15], v[22:25], v[138:141], v[0:15]
	ds_read_b128 v[22:25], v40 offset:12288
	s_waitcnt lgkmcnt(0)
	v_mfma_f32_32x32x16_bf16 v[0:15], v[22:25], v[142:145], v[0:15]
	ds_read_b128 v[22:25], v40 offset:16384
	s_waitcnt lgkmcnt(0)
	v_mfma_f32_32x32x16_bf16 v[0:15], v[22:25], v[146:149], v[0:15]
	ds_read_b128 v[22:25], v40 offset:20480
	s_waitcnt lgkmcnt(0)
	v_mfma_f32_32x32x16_bf16 v[0:15], v[22:25], v[150:153], v[0:15]
	ds_read_b128 v[22:25], v40 offset:24576
	s_waitcnt lgkmcnt(0)
	v_mfma_f32_32x32x16_bf16 v[0:15], v[22:25], v[154:157], v[0:15]
	ds_read_b128 v[22:25], v40 offset:28672
	s_waitcnt lgkmcnt(0)
	v_mfma_f32_32x32x16_bf16 v[0:15], v[22:25], v[158:161], v[0:15]
	v_max_i32_e32 v22, 63, v39
	v_subrev_u32_e32 v22, 63, v22
	v_min_u32_e32 v22, 0x7f, v22
	v_lshl_add_u32 v24, v22, 2, s86
	v_max_i32_e32 v22, 0x4f, v39
	v_add_u32_e32 v22, 0xffffffb1, v22
	v_min_u32_e32 v22, 0x7f, v22
	v_lshl_add_u32 v25, v22, 2, s86
	v_max_i32_e32 v22, 0x5f, v39
	v_add_u32_e32 v22, 0xffffffa1, v22
	v_min_u32_e32 v22, 0x7f, v22
	v_lshl_add_u32 v26, v22, 2, s86
	v_max_i32_e32 v22, 0x6f, v39
	v_add_u32_e32 v22, 0xffffff91, v22
	v_min_u32_e32 v22, 0x7f, v22
	v_lshl_add_u32 v27, v22, 2, s86
	v_max_i32_e32 v22, 0x7f, v39
	v_add_u32_e32 v22, 0xffffff81, v22
	v_min_u32_e32 v22, 0x7f, v22
	v_lshl_add_u32 v28, v22, 2, s86
	v_max_i32_e32 v22, 0x8f, v39
	v_add_u32_e32 v22, 0xffffff71, v22
	v_min_u32_e32 v22, 0x7f, v22
	v_lshl_add_u32 v29, v22, 2, s86
	v_max_i32_e32 v22, 0x11f, v39
	v_add_u32_e32 v22, 0xfffffee1, v22
	v_min_u32_e32 v22, 0x7f, v22
	v_lshl_add_u32 v30, v22, 2, s86
	v_max_i32_e32 v22, 0x12f, v39
	v_add_u32_e32 v22, 0xfffffed1, v22
	v_min_u32_e32 v22, 0x7f, v22
	v_lshl_add_u32 v31, v22, 2, s86
	v_max_i32_e32 v22, 0x13f, v39
	v_add_u32_e32 v22, 0xfffffec1, v22
	v_min_u32_e32 v22, 0x7f, v22
	v_lshl_add_u32 v34, v22, 2, s86
	v_max_i32_e32 v22, 0x14f, v39
	v_add_u32_e32 v22, 0xfffffeb1, v22
	v_min_u32_e32 v22, 0x7f, v22
	v_lshl_add_u32 v35, v22, 2, s86
	v_max_i32_e32 v22, 0x15f, v39
	v_add_u32_e32 v22, 0xfffffea1, v22
	v_min_u32_e32 v22, 0x7f, v22
	v_lshl_add_u32 v36, v22, 2, s86
	v_max_i32_e32 v22, 0x16f, v39
	v_add_u32_e32 v22, 0xfffffe91, v22
	v_min_u32_e32 v22, 0x7f, v22
	v_lshl_add_u32 v37, v22, 2, s86
	v_max_i32_e32 v22, 0x17f, v39
	v_add_u32_e32 v22, 0xfffffe81, v22
	v_min_u32_e32 v22, 0x7f, v22
	v_lshl_add_u32 v38, v22, 2, s86
	v_max_i32_e32 v22, 0x18f, v39
	v_add_u32_e32 v22, 0xfffffe71, v22
	v_min_u32_e32 v22, 0x7f, v22
	v_lshl_add_u32 v41, v22, 2, s86
	ds_read_b32 v22, v17
	ds_read_b32 v23, v21
	ds_read_b32 v24, v24
	ds_read_b32 v25, v25
	ds_read_b32 v26, v26
	ds_read_b32 v27, v27
	ds_read_b32 v21, v28
	ds_read_b32 v28, v29
	ds_read_b32 v42, v30
	ds_read_b32 v43, v31
	ds_read_b32 v44, v34
	ds_read_b32 v45, v35
	ds_read_b32 v46, v36
	ds_read_b32 v47, v37
	ds_read_b32 v48, v38
	ds_read_b32 v41, v41
	v_or_b32_e32 v29, 47, v16
	s_waitcnt lgkmcnt(14)
	v_or_b32_e32 v30, 31, v16
	v_pk_add_f32 v[0:1], v[0:1], v[22:23]
	v_cmp_ge_u32_e32 vcc, v125, v29
	v_or_b32_e32 v23, 0x4f, v16
	s_waitcnt lgkmcnt(13)
	s_waitcnt lgkmcnt(12)
	v_or_b32_e32 v29, 63, v16
	v_cndmask_b32_e32 v38, v231, v1, vcc
	v_cmp_ge_u32_e32 vcc, v125, v30
	s_waitcnt lgkmcnt(11)
	s_waitcnt lgkmcnt(10)
	s_waitcnt lgkmcnt(9)
	s_waitcnt lgkmcnt(8)
	s_waitcnt lgkmcnt(7)
	v_cndmask_b32_e32 v37, v231, v0, vcc
	v_pk_add_f32 v[0:1], v[2:3], v[24:25]
	v_cmp_ge_u32_e32 vcc, v125, v23
	v_max3_f32 v22, v37, s94, v38
	v_or_b32_e32 v3, 0x6f, v16
	v_cndmask_b32_e32 v36, v231, v1, vcc
	v_cmp_ge_u32_e32 vcc, v125, v29
	s_waitcnt lgkmcnt(6)
	s_waitcnt lgkmcnt(5)
	s_waitcnt lgkmcnt(4)
	s_waitcnt lgkmcnt(3)
	s_waitcnt lgkmcnt(2)
	v_cndmask_b32_e32 v35, v231, v0, vcc
	v_max3_f32 v2, v22, v35, v36
	v_or_b32_e32 v22, 0x5f, v16
	v_pk_add_f32 v[0:1], v[4:5], v[26:27]
	v_cmp_ge_u32_e32 vcc, v125, v3
	v_or_b32_e32 v3, 0x12f, v16
	v_or_b32_e32 v4, 0x11f, v16
	v_cndmask_b32_e32 v34, v231, v1, vcc
	v_cmp_ge_u32_e32 vcc, v125, v22
	v_or_b32_e32 v1, 0x7f, v16
	s_waitcnt lgkmcnt(1)
	s_waitcnt lgkmcnt(0)
	v_mov_b32_e32 v17, v16
	v_cndmask_b32_e32 v31, v231, v0, vcc
	v_max3_f32 v0, v2, v31, v34
	v_add_f32_e32 v2, v6, v21
	v_cmp_ge_u32_e32 vcc, v125, v1
	v_add_u32_e32 v1, 0x8f, v16
	s_nop 0
	v_cndmask_b32_e32 v29, v231, v2, vcc
	v_add_f32_e32 v2, v7, v28
	v_cmp_ge_u32_e32 vcc, v125, v1
	s_nop 1
	v_cndmask_b32_e32 v30, v231, v2, vcc
	v_max3_f32 v2, v0, v29, v30
	v_pk_add_f32 v[0:1], v[8:9], v[42:43]
	v_cmp_ge_u32_e32 vcc, v125, v3
	v_or_b32_e32 v3, 0x14f, v16
	s_nop 0
	v_cndmask_b32_e32 v28, v231, v1, vcc
	v_cmp_ge_u32_e32 vcc, v125, v4
	v_or_b32_e32 v4, 0x13f, v16
	s_nop 0
	v_cndmask_b32_e32 v27, v231, v0, vcc
	v_pk_add_f32 v[0:1], v[10:11], v[44:45]
	v_cmp_ge_u32_e32 vcc, v125, v3
	v_or_b32_e32 v3, 0x16f, v16
	v_max3_f32 v2, v2, v27, v28
	v_cndmask_b32_e32 v26, v231, v1, vcc
	v_cmp_ge_u32_e32 vcc, v125, v4
	v_or_b32_e32 v4, 0x15f, v16
	s_nop 0
	v_cndmask_b32_e32 v25, v231, v0, vcc
	v_pk_add_f32 v[0:1], v[12:13], v[46:47]
	v_cmp_ge_u32_e32 vcc, v125, v3
	v_max3_f32 v2, v2, v25, v26
	s_nop 0
	v_cndmask_b32_e32 v24, v231, v1, vcc
	v_cmp_ge_u32_e32 vcc, v125, v4
	v_or_b32_e32 v1, 0x17f, v16
	s_nop 0
	v_cndmask_b32_e32 v23, v231, v0, vcc
	v_max3_f32 v0, v2, v23, v24
	v_add_f32_e32 v2, v14, v48
	v_cmp_ge_u32_e32 vcc, v125, v1
	v_add_u32_e32 v1, 0x18f, v16
	s_nop 0
	v_cndmask_b32_e32 v21, v231, v2, vcc
	v_add_f32_e32 v2, v15, v41
	v_cmp_ge_u32_e32 vcc, v125, v1
	s_nop 1
	v_cndmask_b32_e32 v22, v231, v2, vcc
	v_max3_f32 v41, v0, v21, v22
	s_cbranch_scc1 .LBB0_1081
	ds_read_b128 v[0:3], v40 offset:512
	ds_read_b128 v[42:45], v40 offset:4608
	v_max_i32_e32 v46, 0x25f, v39
	v_max_i32_e32 v47, 0x26f, v39
	v_max_i32_e32 v48, 0x27f, v39
	v_max_i32_e32 v49, 0x28f, v39
	v_max_i32_e32 v50, 0x31f, v39
	v_max_i32_e32 v51, 0x32f, v39
	v_max_i32_e32 v52, 0x33f, v39
	s_waitcnt lgkmcnt(1)
	v_mfma_f32_32x32x16_bf16 v[0:15], v[0:3], v[130:133], 0
	v_max_i32_e32 v53, 0x34f, v39
	v_max_i32_e32 v54, 0x35f, v39
	v_max_i32_e32 v55, 0x36f, v39
	v_max_i32_e32 v56, 0x37f, v39
	v_add_u32_e32 v46, 0xfffffda1, v46
	v_add_u32_e32 v47, 0xfffffd91, v47
	v_add_u32_e32 v48, 0xfffffd81, v48
	s_waitcnt lgkmcnt(0)
	v_mfma_f32_32x32x16_bf16 v[0:15], v[42:45], v[134:137], v[0:15]
	ds_read_b128 v[42:45], v40 offset:8704
	v_add_u32_e32 v49, 0xfffffd71, v49
	v_add_u32_e32 v50, 0xfffffce1, v50
	v_add_u32_e32 v51, 0xfffffcd1, v51
	v_add_u32_e32 v52, 0xfffffcc1, v52
	v_add_u32_e32 v53, 0xfffffcb1, v53
	v_add_u32_e32 v54, 0xfffffca1, v54
	v_add_u32_e32 v55, 0xfffffc91, v55
	s_waitcnt lgkmcnt(0)
	v_mfma_f32_32x32x16_bf16 v[0:15], v[42:45], v[138:141], v[0:15]
	ds_read_b128 v[42:45], v40 offset:12800
	v_add_u32_e32 v56, 0xfffffc81, v56
	v_max_i32_e32 v57, 0x38f, v39
	v_min_u32_e32 v46, 0x7f, v46
	v_min_u32_e32 v47, 0x7f, v47
	v_min_u32_e32 v48, 0x7f, v48
	v_min_u32_e32 v49, 0x7f, v49
	s_waitcnt lgkmcnt(0)
	v_mfma_f32_32x32x16_bf16 v[0:15], v[42:45], v[142:145], v[0:15]
	ds_read_b128 v[42:45], v40 offset:16896
	v_min_u32_e32 v50, 0x7f, v50
	v_min_u32_e32 v51, 0x7f, v51
	v_min_u32_e32 v52, 0x7f, v52
	v_min_u32_e32 v53, 0x7f, v53
	v_min_u32_e32 v54, 0x7f, v54
	v_min_u32_e32 v55, 0x7f, v55
	s_waitcnt lgkmcnt(0)
	v_mfma_f32_32x32x16_bf16 v[0:15], v[42:45], v[146:149], v[0:15]
	ds_read_b128 v[42:45], v40 offset:20992
	v_min_u32_e32 v56, 0x7f, v56
	v_add_u32_e32 v57, 0xfffffc71, v57
	v_lshl_add_u32 v46, v46, 2, s86
	v_lshl_add_u32 v47, v47, 2, s86
	v_lshl_add_u32 v48, v48, 2, s86
	v_lshl_add_u32 v49, v49, 2, s86
	s_waitcnt lgkmcnt(0)
	v_mfma_f32_32x32x16_bf16 v[0:15], v[42:45], v[150:153], v[0:15]
	ds_read_b128 v[42:45], v40 offset:25088
	v_lshl_add_u32 v50, v50, 2, s86
	v_lshl_add_u32 v51, v51, 2, s86
	v_lshl_add_u32 v52, v52, 2, s86
	v_lshl_add_u32 v53, v53, 2, s86
	v_lshl_add_u32 v54, v54, 2, s86
	v_lshl_add_u32 v55, v55, 2, s86
	s_waitcnt lgkmcnt(0)
	v_mfma_f32_32x32x16_bf16 v[0:15], v[42:45], v[154:157], v[0:15]
	ds_read_b128 v[42:45], v40 offset:29184
	v_lshl_add_u32 v56, v56, 2, s86
	v_min_u32_e32 v57, 0x7f, v57
	v_lshl_add_u32 v57, v57, 2, s86
	s_waitcnt lgkmcnt(0)
	v_mfma_f32_32x32x16_bf16 v[0:15], v[42:45], v[158:161], v[0:15]
	v_max_i32_e32 v42, 0x21f, v39
	v_max_i32_e32 v43, 0x22f, v39
	v_max_i32_e32 v44, 0x23f, v39
	v_max_i32_e32 v45, 0x24f, v39
	v_add_u32_e32 v42, 0xfffffde1, v42
	v_add_u32_e32 v43, 0xfffffdd1, v43
	v_add_u32_e32 v44, 0xfffffdc1, v44
	v_add_u32_e32 v45, 0xfffffdb1, v45
	v_min_u32_e32 v42, 0x7f, v42
	v_min_u32_e32 v43, 0x7f, v43
	v_min_u32_e32 v44, 0x7f, v44
	v_min_u32_e32 v45, 0x7f, v45
	v_lshl_add_u32 v42, v42, 2, s86
	v_lshl_add_u32 v43, v43, 2, s86
	v_lshl_add_u32 v44, v44, 2, s86
	v_lshl_add_u32 v45, v45, 2, s86
	ds_read_b32 v42, v42
	ds_read_b32 v43, v43
	ds_read_b32 v44, v44
	ds_read_b32 v45, v45
	ds_read_b32 v46, v46
	ds_read_b32 v47, v47
	ds_read_b32 v58, v48
	ds_read_b32 v59, v49
	ds_read_b32 v48, v50
	ds_read_b32 v49, v51
	ds_read_b32 v50, v52
	ds_read_b32 v51, v53
	ds_read_b32 v52, v54
	ds_read_b32 v53, v55
	ds_read_b32 v54, v56
	ds_read_b32 v55, v57
	v_or_b32_e32 v56, 0x22f, v17
	s_waitcnt lgkmcnt(14)
	v_or_b32_e32 v57, 0x21f, v16
	v_pk_add_f32 v[0:1], v[0:1], v[42:43]
	v_cmp_ge_u32_e32 vcc, v125, v56
	v_or_b32_e32 v42, 0x24f, v17
	s_waitcnt lgkmcnt(13)
	s_waitcnt lgkmcnt(12)
	v_or_b32_e32 v43, 0x23f, v16
	v_cndmask_b32_e32 v67, v231, v1, vcc
	v_cmp_ge_u32_e32 vcc, v125, v57
	s_waitcnt lgkmcnt(11)
	s_waitcnt lgkmcnt(10)
	s_waitcnt lgkmcnt(9)
	s_waitcnt lgkmcnt(8)
	s_waitcnt lgkmcnt(7)
	v_cndmask_b32_e32 v66, v231, v0, vcc
	v_pk_add_f32 v[0:1], v[2:3], v[44:45]
	v_cmp_ge_u32_e32 vcc, v125, v42
	v_max3_f32 v41, v41, v66, v67
	v_or_b32_e32 v3, 0x26f, v17
	v_cndmask_b32_e32 v69, v231, v1, vcc
	v_cmp_ge_u32_e32 vcc, v125, v43
	s_waitcnt lgkmcnt(6)
	s_waitcnt lgkmcnt(5)
	s_waitcnt lgkmcnt(4)
	s_waitcnt lgkmcnt(3)
	s_waitcnt lgkmcnt(2)
	v_cndmask_b32_e32 v68, v231, v0, vcc
	v_max3_f32 v2, v41, v68, v69
	v_or_b32_e32 v41, 0x25f, v16
	v_pk_add_f32 v[0:1], v[4:5], v[46:47]
	v_cmp_ge_u32_e32 vcc, v125, v3
	v_or_b32_e32 v3, 0x32f, v17
	v_or_b32_e32 v4, 0x31f, v16
	v_cndmask_b32_e32 v71, v231, v1, vcc
	v_cmp_ge_u32_e32 vcc, v125, v41
	v_or_b32_e32 v1, 0x27f, v16
	s_waitcnt lgkmcnt(1)
	s_waitcnt lgkmcnt(0)
	v_cndmask_b32_e32 v70, v231, v0, vcc
	v_max3_f32 v0, v2, v70, v71
	v_add_f32_e32 v2, v6, v58
	v_cmp_ge_u32_e32 vcc, v125, v1
	v_add_u32_e32 v1, 0x28f, v16
	s_nop 0
	v_cndmask_b32_e32 v72, v231, v2, vcc
	v_add_f32_e32 v2, v7, v59
	v_cmp_ge_u32_e32 vcc, v125, v1
	s_nop 1
	v_cndmask_b32_e32 v73, v231, v2, vcc
	v_max3_f32 v2, v0, v72, v73
	v_pk_add_f32 v[0:1], v[8:9], v[48:49]
	v_cmp_ge_u32_e32 vcc, v125, v3
	v_or_b32_e32 v3, 0x34f, v17
	s_nop 0
	v_cndmask_b32_e32 v75, v231, v1, vcc
	v_cmp_ge_u32_e32 vcc, v125, v4
	v_or_b32_e32 v4, 0x33f, v16
	s_nop 0
	v_cndmask_b32_e32 v74, v231, v0, vcc
	v_pk_add_f32 v[0:1], v[10:11], v[50:51]
	v_cmp_ge_u32_e32 vcc, v125, v3
	v_or_b32_e32 v3, 0x36f, v17
	v_max3_f32 v2, v2, v74, v75
	v_cndmask_b32_e32 v77, v231, v1, vcc
	v_cmp_ge_u32_e32 vcc, v125, v4
	v_or_b32_e32 v4, 0x35f, v16
	s_nop 0
	v_cndmask_b32_e32 v76, v231, v0, vcc
	v_pk_add_f32 v[0:1], v[12:13], v[52:53]
	v_cmp_ge_u32_e32 vcc, v125, v3
	v_max3_f32 v2, v2, v76, v77
	s_nop 0
	v_cndmask_b32_e32 v79, v231, v1, vcc
	v_cmp_ge_u32_e32 vcc, v125, v4
	v_or_b32_e32 v1, 0x37f, v16
	s_nop 0
	v_cndmask_b32_e32 v78, v231, v0, vcc
	v_max3_f32 v0, v2, v78, v79
	v_add_f32_e32 v2, v14, v54
	v_cmp_ge_u32_e32 vcc, v125, v1
	v_add_u32_e32 v1, 0x38f, v16
	s_nop 0
	v_cndmask_b32_e32 v80, v231, v2, vcc
	v_add_f32_e32 v2, v15, v55
	v_cmp_ge_u32_e32 vcc, v125, v1
	s_nop 1
	v_cndmask_b32_e32 v81, v231, v2, vcc
	v_max3_f32 v41, v0, v80, v81
	s_cmp_gt_u32 s79, 15
	s_cselect_b64 s[6:7], -1, 0
	s_cmp_lt_u32 s79, 16
	s_cbranch_scc0 .LBB0_1082
